# w_out tile epilogue: the residual x rows (read once) are loaded non-temporal
# speedup vs baseline: 1.0073x; 1.0073x over previous
.LBB0_1499:
	s_andn2_b64 vcc, exec, s[42:43]
	s_cbranch_vccnz .LBB0_1501
	s_ashr_i32 s4, s38, 4
	s_mul_hi_i32 s27, s4, 0x18000
	s_mul_i32 s4, s4, 0x18000
	s_add_u32 s42, s10, s4
	s_addc_u32 s43, s11, s27
	s_ashr_i32 s39, s38, 31
	s_lshl_b64 s[38:39], s[38:39], 8
	s_add_u32 s38, s38, s68
	v_lshlrev_b64 v[14:15], 2, v[2:3]
	v_ashrrev_i32_e32 v5, 31, v4
	s_addc_u32 s39, s39, 0
	v_lshl_add_u64 v[16:17], s[42:43], 0, v[14:15]
	v_lshl_add_u64 v[22:23], s[38:39], 0, v[4:5]
	global_load_dwordx4 v[6:9], v[16:17], off
	global_load_dwordx4 v[10:13], v[16:17], off offset:64
	global_load_dwordx4 v[24:27], v[16:17], off offset:512
	global_load_dwordx4 v[28:31], v[16:17], off offset:576
	v_lshl_add_u64 v[20:21], s[56:57], 0, v[14:15]
	v_lshlrev_b64 v[4:5], 14, v[22:23]
	v_lshl_add_u64 v[4:5], v[20:21], 0, v[4:5]
	global_load_dwordx4 v[172:175], v[4:5], off nt
	global_load_dwordx4 v[176:179], v[4:5], off offset:64 nt
	global_load_dwordx4 v[186:189], v[4:5], off offset:512 nt
	global_load_dwordx4 v[190:193], v[4:5], off offset:576 nt
	v_lshl_add_u64 v[4:5], v[22:23], 0, 16
	v_lshlrev_b64 v[14:15], 14, v[4:5]
	v_lshl_add_u64 v[14:15], v[20:21], 0, v[14:15]
	global_load_dwordx4 v[194:197], v[14:15], off nt
	global_load_dwordx4 v[198:201], v[14:15], off offset:64 nt
	global_load_dwordx4 v[202:205], v[14:15], off offset:512 nt
	global_load_dwordx4 v[206:209], v[14:15], off offset:576 nt
	v_lshl_add_u64 v[32:33], v[22:23], 0, 32
	v_lshlrev_b64 v[14:15], 14, v[32:33]
	v_lshl_add_u64 v[14:15], v[20:21], 0, v[14:15]
	global_load_dwordx4 v[210:213], v[14:15], off nt
	global_load_dwordx4 v[214:217], v[14:15], off offset:64 nt
	global_load_dwordx4 v[218:221], v[14:15], off offset:512 nt
	v_lshl_add_u64 v[242:243], v[22:23], 0, 48
	global_load_dwordx4 v[222:225], v[14:15], off offset:576 nt
	v_lshlrev_b64 v[16:17], 14, v[242:243]
	v_lshl_add_u64 v[16:17], v[20:21], 0, v[16:17]
	global_load_dwordx4 v[226:229], v[16:17], off nt
	global_load_dwordx4 v[230:233], v[16:17], off offset:64 nt
	global_load_dwordx4 v[234:237], v[16:17], off offset:512 nt
	global_load_dwordx4 v[238:241], v[16:17], off offset:576 nt
	v_lshlrev_b64 v[14:15], 13, v[22:23]
	v_lshlrev_b64 v[2:3], 1, v[2:3]
	v_lshl_add_u64 v[14:15], s[8:9], 0, v[14:15]
	v_lshlrev_b64 v[4:5], 13, v[4:5]
	v_lshl_add_u64 v[244:245], v[14:15], 0, v[2:3]
	v_lshl_add_u64 v[4:5], s[8:9], 0, v[4:5]
	v_lshl_add_u64 v[246:247], v[4:5], 0, v[2:3]
	s_mov_b64 s[38:39], 0x90
	s_waitcnt vmcnt(0)
	v_pk_mul_f32 v[18:19], v[6:7], s[20:21] op_sel_hi:[1,0]
	v_pk_mul_f32 v[16:17], v[8:9], s[20:21] op_sel_hi:[1,0]
	v_pk_mul_f32 v[8:9], v[26:27], s[20:21] op_sel_hi:[1,0]
	v_pk_mul_f32 v[12:13], v[12:13], s[20:21] op_sel_hi:[1,0]
	v_pk_fma_f32 v[26:27], v[158:159], v[18:19], v[172:173]
	v_pk_mul_f32 v[14:15], v[10:11], s[20:21] op_sel_hi:[1,0]
	v_pk_mul_f32 v[10:11], v[24:25], s[20:21] op_sel_hi:[1,0]
	v_pk_fma_f32 v[24:25], v[160:161], v[16:17], v[174:175]
	v_cvt_pk_bf16_f32 v26, v26, v27
	v_pk_mul_f32 v[4:5], v[30:31], s[20:21] op_sel_hi:[1,0]
	v_cvt_pk_bf16_f32 v27, v24, v25
	v_pk_mul_f32 v[6:7], v[28:29], s[20:21] op_sel_hi:[1,0]
	v_pk_fma_f32 v[28:29], v[156:157], v[12:13], v[178:179]
	v_pk_fma_f32 v[30:31], v[154:155], v[14:15], v[176:177]
	global_store_dwordx2 v[244:245], v[26:27], off
	v_cvt_pk_bf16_f32 v26, v30, v31
	v_cvt_pk_bf16_f32 v27, v28, v29
	v_pk_fma_f32 v[144:145], v[144:145], v[8:9], v[188:189]
	v_pk_fma_f32 v[142:143], v[142:143], v[10:11], v[186:187]
	global_store_dwordx2 v[244:245], v[26:27], off offset:32
	v_cvt_pk_bf16_f32 v26, v142, v143
	v_cvt_pk_bf16_f32 v27, v144, v145
	v_pk_fma_f32 v[140:141], v[140:141], v[4:5], v[192:193]
	v_pk_fma_f32 v[138:139], v[138:139], v[6:7], v[190:191]
	v_pk_fma_f32 v[24:25], v[152:153], v[16:17], v[196:197]
	global_store_dwordx2 v[244:245], v[26:27], off offset:256
	v_cvt_pk_bf16_f32 v26, v138, v139
	v_cvt_pk_bf16_f32 v27, v140, v141
	v_pk_fma_f32 v[150:151], v[150:151], v[18:19], v[194:195]
	v_pk_fma_f32 v[148:149], v[148:149], v[12:13], v[200:201]
	v_pk_fma_f32 v[146:147], v[146:147], v[14:15], v[198:199]
	global_store_dwordx2 v[244:245], v[26:27], off offset:288
	v_cvt_pk_bf16_f32 v26, v150, v151
	v_cvt_pk_bf16_f32 v27, v24, v25
	global_store_dwordx2 v[246:247], v[26:27], off
	v_cvt_pk_bf16_f32 v24, v146, v147
	v_cvt_pk_bf16_f32 v25, v148, v149
	v_pk_fma_f32 v[136:137], v[136:137], v[8:9], v[204:205]
	v_pk_fma_f32 v[134:135], v[134:135], v[10:11], v[202:203]
	global_store_dwordx2 v[246:247], v[24:25], off offset:32
	v_cvt_pk_bf16_f32 v24, v134, v135
	v_cvt_pk_bf16_f32 v25, v136, v137
	v_pk_fma_f32 v[132:133], v[132:133], v[4:5], v[208:209]
	v_pk_fma_f32 v[130:131], v[130:131], v[6:7], v[206:207]
	global_store_dwordx2 v[246:247], v[24:25], off offset:256
	v_cvt_pk_bf16_f32 v24, v130, v131
	v_cvt_pk_bf16_f32 v25, v132, v133
	global_store_dwordx2 v[246:247], v[24:25], off offset:288
	v_lshlrev_b64 v[24:25], 13, v[32:33]
	v_pk_fma_f32 v[28:29], v[126:127], v[18:19], v[210:211]
	v_lshl_add_u64 v[24:25], s[8:9], 0, v[24:25]
	v_pk_fma_f32 v[26:27], v[128:129], v[16:17], v[212:213]
	v_cvt_pk_bf16_f32 v28, v28, v29
	v_lshl_add_u64 v[24:25], v[24:25], 0, v[2:3]
	v_cvt_pk_bf16_f32 v29, v26, v27
	global_store_dwordx2 v[24:25], v[28:29], off
	v_pk_fma_f32 v[28:29], v[122:123], v[14:15], v[214:215]
	v_pk_fma_f32 v[26:27], v[124:125], v[12:13], v[216:217]
	v_cvt_pk_bf16_f32 v28, v28, v29
	v_lshl_add_u64 v[32:33], v[22:23], 0, s[12:13]
	v_cvt_pk_bf16_f32 v29, v26, v27
	global_store_dwordx2 v[24:25], v[28:29], off offset:32
	v_pk_fma_f32 v[28:29], v[118:119], v[10:11], v[218:219]
	v_pk_fma_f32 v[26:27], v[120:121], v[8:9], v[220:221]
	v_cvt_pk_bf16_f32 v28, v28, v29
	v_lshl_add_u64 v[150:151], v[22:23], 0, s[38:39]
	v_cvt_pk_bf16_f32 v29, v26, v27
	global_store_dwordx2 v[24:25], v[28:29], off offset:256
	v_pk_fma_f32 v[28:29], v[110:111], v[6:7], v[222:223]
	v_pk_fma_f32 v[26:27], v[112:113], v[4:5], v[224:225]
	v_cvt_pk_bf16_f32 v28, v28, v29
	s_mov_b64 s[38:39], 0xa0
	v_cvt_pk_bf16_f32 v29, v26, v27
	global_store_dwordx2 v[24:25], v[28:29], off offset:288
	v_lshlrev_b64 v[24:25], 13, v[242:243]
	v_pk_fma_f32 v[28:29], v[114:115], v[18:19], v[226:227]
	v_lshl_add_u64 v[24:25], s[8:9], 0, v[24:25]
	v_pk_fma_f32 v[26:27], v[116:117], v[16:17], v[228:229]
	v_cvt_pk_bf16_f32 v28, v28, v29
	v_lshl_add_u64 v[24:25], v[24:25], 0, v[2:3]
	v_cvt_pk_bf16_f32 v29, v26, v27
	global_store_dwordx2 v[24:25], v[28:29], off
	v_pk_fma_f32 v[28:29], v[106:107], v[14:15], v[230:231]
	v_pk_fma_f32 v[26:27], v[108:109], v[12:13], v[232:233]
	v_cvt_pk_bf16_f32 v28, v28, v29
	v_lshlrev_b64 v[106:107], 14, v[150:151]
	v_cvt_pk_bf16_f32 v29, v26, v27
	global_store_dwordx2 v[24:25], v[28:29], off offset:32
	v_pk_fma_f32 v[28:29], v[102:103], v[10:11], v[234:235]
	v_pk_fma_f32 v[26:27], v[104:105], v[8:9], v[236:237]
	v_cvt_pk_bf16_f32 v28, v28, v29
	v_lshl_add_u64 v[118:119], v[20:21], 0, v[106:107]
	v_cvt_pk_bf16_f32 v29, v26, v27
	global_store_dwordx2 v[24:25], v[28:29], off offset:256
	v_pk_fma_f32 v[28:29], v[98:99], v[6:7], v[238:239]
	v_pk_fma_f32 v[26:27], v[100:101], v[4:5], v[240:241]
	v_cvt_pk_bf16_f32 v28, v28, v29
	v_lshl_add_u64 v[152:153], v[22:23], 0, s[38:39]
	v_cvt_pk_bf16_f32 v29, v26, v27
	global_store_dwordx2 v[24:25], v[28:29], off offset:288
	v_lshlrev_b64 v[24:25], 14, v[32:33]
	v_lshl_add_u64 v[102:103], v[20:21], 0, v[24:25]
	global_load_dwordx4 v[24:27], v[102:103], off nt
	global_load_dwordx4 v[28:31], v[102:103], off offset:64 nt
	global_load_dwordx4 v[98:101], v[102:103], off offset:512 nt
	s_nop 0
	global_load_dwordx4 v[102:105], v[102:103], off offset:576 nt
	s_nop 0
	global_load_dwordx4 v[106:109], v[118:119], off nt
	global_load_dwordx4 v[110:113], v[118:119], off offset:64 nt
	global_load_dwordx4 v[114:117], v[118:119], off offset:512 nt
	s_nop 0
	global_load_dwordx4 v[118:121], v[118:119], off offset:576 nt
	v_lshlrev_b64 v[122:123], 14, v[152:153]
	v_lshl_add_u64 v[134:135], v[20:21], 0, v[122:123]
	global_load_dwordx4 v[122:125], v[134:135], off nt
	global_load_dwordx4 v[126:129], v[134:135], off offset:64 nt
	global_load_dwordx4 v[130:133], v[134:135], off offset:512 nt
	s_nop 0
	global_load_dwordx4 v[134:137], v[134:135], off offset:576 nt
	s_mov_b64 s[38:39], 0xb0
	v_lshl_add_u64 v[154:155], v[22:23], 0, s[38:39]
	v_lshlrev_b64 v[22:23], 14, v[154:155]
	v_lshl_add_u64 v[146:147], v[20:21], 0, v[22:23]
	global_load_dwordx4 v[20:23], v[146:147], off nt
	global_load_dwordx4 v[138:141], v[146:147], off offset:64 nt
	global_load_dwordx4 v[142:145], v[146:147], off offset:512 nt
	s_nop 0
	global_load_dwordx4 v[146:149], v[146:147], off offset:576 nt
	v_lshlrev_b64 v[32:33], 13, v[32:33]
	v_lshl_add_u64 v[32:33], s[8:9], 0, v[32:33]
	v_lshl_add_u64 v[32:33], v[32:33], 0, v[2:3]
	s_waitcnt vmcnt(15)
	v_pk_fma_f32 v[24:25], v[94:95], v[18:19], v[24:25]
	v_pk_fma_f32 v[26:27], v[96:97], v[16:17], v[26:27]
	v_cvt_pk_bf16_f32 v24, v24, v25
	s_waitcnt vmcnt(14)
	v_pk_fma_f32 v[30:31], v[92:93], v[12:13], v[30:31]
	v_cvt_pk_bf16_f32 v25, v26, v27
	v_pk_fma_f32 v[28:29], v[90:91], v[14:15], v[28:29]
	global_store_dwordx2 v[32:33], v[24:25], off
	v_cvt_pk_bf16_f32 v24, v28, v29
	v_cvt_pk_bf16_f32 v25, v30, v31
	s_waitcnt vmcnt(14)
	v_pk_fma_f32 v[88:89], v[88:89], v[8:9], v[100:101]
	v_pk_fma_f32 v[86:87], v[86:87], v[10:11], v[98:99]
	global_store_dwordx2 v[32:33], v[24:25], off offset:32
	v_cvt_pk_bf16_f32 v24, v86, v87
	v_cvt_pk_bf16_f32 v25, v88, v89
	global_store_dwordx2 v[32:33], v[24:25], off offset:256
	s_waitcnt vmcnt(15)
	v_pk_fma_f32 v[24:25], v[78:79], v[6:7], v[102:103]
	v_pk_fma_f32 v[80:81], v[80:81], v[4:5], v[104:105]
	v_cvt_pk_bf16_f32 v24, v24, v25
	s_waitcnt vmcnt(14)
	v_pk_fma_f32 v[28:29], v[82:83], v[18:19], v[106:107]
	v_cvt_pk_bf16_f32 v25, v80, v81
	global_store_dwordx2 v[32:33], v[24:25], off offset:288
	v_lshlrev_b64 v[24:25], 13, v[150:151]
	v_lshl_add_u64 v[24:25], s[8:9], 0, v[24:25]
	v_pk_fma_f32 v[26:27], v[84:85], v[16:17], v[108:109]
	v_cvt_pk_bf16_f32 v28, v28, v29
	v_lshl_add_u64 v[24:25], v[24:25], 0, v[2:3]
	v_cvt_pk_bf16_f32 v29, v26, v27
	global_store_dwordx2 v[24:25], v[28:29], off
	s_waitcnt vmcnt(15)
	v_pk_fma_f32 v[28:29], v[74:75], v[14:15], v[110:111]
	v_pk_fma_f32 v[26:27], v[76:77], v[12:13], v[112:113]
	v_cvt_pk_bf16_f32 v28, v28, v29
	s_nop 0
	v_cvt_pk_bf16_f32 v29, v26, v27
	global_store_dwordx2 v[24:25], v[28:29], off offset:32
	s_waitcnt vmcnt(15)
	v_pk_fma_f32 v[28:29], v[70:71], v[10:11], v[114:115]
	v_pk_fma_f32 v[26:27], v[72:73], v[8:9], v[116:117]
	v_cvt_pk_bf16_f32 v28, v28, v29
	s_nop 0
	v_cvt_pk_bf16_f32 v29, v26, v27
	global_store_dwordx2 v[24:25], v[28:29], off offset:256
	s_waitcnt vmcnt(15)
	v_pk_fma_f32 v[28:29], v[62:63], v[6:7], v[118:119]
	v_pk_fma_f32 v[26:27], v[64:65], v[4:5], v[120:121]
	v_cvt_pk_bf16_f32 v28, v28, v29
	s_nop 0
	v_cvt_pk_bf16_f32 v29, v26, v27
	global_store_dwordx2 v[24:25], v[28:29], off offset:288
	v_lshlrev_b64 v[24:25], 13, v[152:153]
	s_waitcnt vmcnt(15)
	v_pk_fma_f32 v[28:29], v[66:67], v[18:19], v[122:123]
	v_lshl_add_u64 v[24:25], s[8:9], 0, v[24:25]
	v_pk_fma_f32 v[26:27], v[68:69], v[16:17], v[124:125]
	v_cvt_pk_bf16_f32 v28, v28, v29
	v_lshl_add_u64 v[24:25], v[24:25], 0, v[2:3]
	v_cvt_pk_bf16_f32 v29, v26, v27
	global_store_dwordx2 v[24:25], v[28:29], off
	s_waitcnt vmcnt(15)
	v_pk_fma_f32 v[28:29], v[58:59], v[14:15], v[126:127]
	v_pk_fma_f32 v[26:27], v[60:61], v[12:13], v[128:129]
	v_cvt_pk_bf16_f32 v28, v28, v29
	s_waitcnt vmcnt(12)
	v_pk_fma_f32 v[16:17], v[52:53], v[16:17], v[22:23]
	v_cvt_pk_bf16_f32 v29, v26, v27
	global_store_dwordx2 v[24:25], v[28:29], off offset:32
	v_pk_fma_f32 v[28:29], v[54:55], v[10:11], v[130:131]
	v_pk_fma_f32 v[26:27], v[56:57], v[8:9], v[132:133]
	v_cvt_pk_bf16_f32 v28, v28, v29
	v_pk_fma_f32 v[18:19], v[50:51], v[18:19], v[20:21]
	v_cvt_pk_bf16_f32 v29, v26, v27
	global_store_dwordx2 v[24:25], v[28:29], off offset:256
	v_pk_fma_f32 v[28:29], v[46:47], v[6:7], v[134:135]
	v_pk_fma_f32 v[26:27], v[48:49], v[4:5], v[136:137]
	v_cvt_pk_bf16_f32 v28, v28, v29
	s_waitcnt vmcnt(13)
	v_pk_fma_f32 v[14:15], v[42:43], v[14:15], v[138:139]
	v_cvt_pk_bf16_f32 v29, v26, v27
	global_store_dwordx2 v[24:25], v[28:29], off offset:288
	v_lshlrev_b64 v[24:25], 13, v[154:155]
	v_cvt_pk_bf16_f32 v18, v18, v19
	v_cvt_pk_bf16_f32 v19, v16, v17
	v_lshl_add_u64 v[16:17], s[8:9], 0, v[24:25]
	v_lshl_add_u64 v[2:3], v[16:17], 0, v[2:3]
	s_waitcnt vmcnt(13)
	v_pk_fma_f32 v[10:11], v[38:39], v[10:11], v[142:143]
	s_waitcnt vmcnt(12)
	v_pk_fma_f32 v[6:7], v[34:35], v[6:7], v[146:147]
	global_store_dwordx2 v[2:3], v[18:19], off
	v_pk_fma_f32 v[12:13], v[44:45], v[12:13], v[140:141]
	v_cvt_pk_bf16_f32 v14, v14, v15
	v_pk_fma_f32 v[8:9], v[40:41], v[8:9], v[144:145]
	v_cvt_pk_bf16_f32 v15, v12, v13
	global_store_dwordx2 v[2:3], v[14:15], off offset:32
	v_cvt_pk_bf16_f32 v10, v10, v11
	v_cvt_pk_bf16_f32 v11, v8, v9
	global_store_dwordx2 v[2:3], v[10:11], off offset:256
	v_pk_fma_f32 v[4:5], v[36:37], v[4:5], v[148:149]
	v_cvt_pk_bf16_f32 v6, v6, v7
	s_nop 0
	v_cvt_pk_bf16_f32 v7, v4, v5
	global_store_dwordx2 v[2:3], v[6:7], off offset:288
